# + m9c: PLE GEMM epilogue keeps 5 pieces of gate/residual loads in flight (rolling window over dead fragment registers) instead of load-wait-store per piece
# speedup vs baseline: 1.0120x; 1.0071x over previous
;     __device__ __forceinline__ void operator()(const pg8::f32x4 (&acc)[2][2][4][2], const pg8::Unit& u, int wr, int wc, int fr, int fq) const {
;     ...
;         for (int ai = 0; ai < 2; ++ai)
; #pragma unroll
;             for (int m = 0; m < 4; ++m) {
;                 const int row = u.pm * 256 + ai * 128 + wr * 64 + m * 16 + fr;
; #pragma unroll
;                 for (int bj = 0; bj < 2; ++bj) {
;                     const int col = u.pn * 256 + bj * 128 + wc * 32 + 8 * fq;
;                     f(w, row, col, acc[ai][bj][m][0], acc[ai][bj][m][1]);
;                 }
.LBB0_63:
	v_mov_b32_e32 v135, v222
	s_lshl_b32 s23, s78, 8
	v_readfirstlane_b32 s21, v135
	s_ashr_i32 s55, s21, 2
	s_lshr_b32 s21, s21, 1
	s_andn2_b32 s55, s55, 63
	v_and_or_b32 v134, v135, 15, s23
	s_lshl_b32 s23, s54, 8
	s_and_b32 s21, s21, 0x60
	s_mov_b64 s[70:71], s[8:9]
	v_add_u32_e32 v134, s55, v134
	s_or_b32 s21, s21, s23
	v_lshrrev_b32_e32 v135, 1, v135
	v_and_or_b32 v136, v135, 24, s21
	s_add_u32 s78, s70, 0x4a00000
	v_ashrrev_i32_e32 v135, 31, v134
	s_addc_u32 s79, s71, 0
	v_lshlrev_b64 v[138:139], 11, v[134:135]
	v_ashrrev_i32_e32 v137, 31, v136
	v_lshl_add_u64 v[142:143], s[78:79], 0, v[138:139]
	v_lshlrev_b64 v[138:139], 1, v[136:137]
	v_lshl_add_u64 v[154:155], v[142:143], 0, v[138:139]
	v_lshlrev_b64 v[146:147], 12, v[134:135]
	v_mov_b64_e32 v[162:163], v[154:155]
	v_lshl_add_u64 v[146:147], s[10:11], 0, v[146:147]
	v_lshlrev_b64 v[136:137], 2, v[136:137]
	v_lshl_add_u64 v[156:157], v[146:147], 0, v[136:137]
	v_mov_b64_e32 v[206:207], v[156:157]
	global_load_dwordx4 v[164:167], v[162:163], off
	global_load_dwordx4 v[168:171], v[206:207], off
	global_load_dwordx4 v[172:175], v[206:207], off offset:16
	global_load_dwordx4 v[176:179], v[162:163], off offset:256
	global_load_dwordx4 v[180:183], v[206:207], off offset:512
	global_load_dwordx4 v[184:187], v[206:207], off offset:528
	s_mov_b64 s[98:99], 0x8000
	v_lshl_add_u64 v[220:221], v[162:163], 0, s[98:99]
	global_load_dwordx4 v[188:191], v[220:221], off
	s_mov_b64 s[98:99], 0x10000
	v_lshl_add_u64 v[226:227], v[206:207], 0, s[98:99]
	global_load_dwordx4 v[194:197], v[226:227], off
	global_load_dwordx4 v[202:205], v[226:227], off offset:16
	s_mov_b64 s[98:99], 0x8000
	v_lshl_add_u64 v[220:221], v[162:163], 0, s[98:99]
	global_load_dwordx4 v[212:215], v[220:221], off offset:256
	s_mov_b64 s[98:99], 0x10000
	v_lshl_add_u64 v[226:227], v[206:207], 0, s[98:99]
	global_load_dwordx4 v[216:219], v[226:227], off offset:512
	global_load_dwordx4 v[230:233], v[226:227], off offset:528
	s_mov_b64 s[98:99], 0x10000
	v_lshl_add_u64 v[220:221], v[162:163], 0, s[98:99]
	global_load_dwordx4 v[234:237], v[220:221], off
	s_mov_b64 s[98:99], 0x20000
	v_lshl_add_u64 v[226:227], v[206:207], 0, s[98:99]
	global_load_dwordx4 v[238:241], v[226:227], off
	global_load_dwordx4 v[242:245], v[226:227], off offset:16
	s_andn2_b64 vcc, exec, s[6:7]
	s_mov_b64 s[6:7], -1
	s_mov_b64 s[72:73], 0x20000
	v_mov_b64_e32 v[208:209], v[252:253]
	v_mov_b64_e32 v[224:225], v[198:199]
	v_mov_b64_e32 v[198:199], v[200:201]
	v_mov_b64_e32 v[200:201], v[228:229]
	v_mov_b64_e32 v[228:229], 0xb00
	v_mov_b64_e32 v[250:251], 0xaff
	v_mov_b64_e32 v[252:253], 0x800
	s_waitcnt vmcnt(14)
	v_lshlrev_b32_e32 v158, 16, v164
	v_and_b32_e32 v159, 0xffff0000, v164
	v_lshlrev_b32_e32 v142, 16, v165
	v_and_b32_e32 v143, 0xffff0000, v165
	v_lshlrev_b32_e32 v160, 16, v166
	v_and_b32_e32 v161, 0xffff0000, v166
	v_lshlrev_b32_e32 v144, 16, v167
	v_and_b32_e32 v145, 0xffff0000, v167
	s_waitcnt vmcnt(13)
	v_pk_fma_f32 v[126:127], v[126:127], v[142:143], v[170:171]
	v_pk_fma_f32 v[124:125], v[124:125], v[158:159], v[168:169]
	s_waitcnt vmcnt(12)
	v_pk_fma_f32 v[122:123], v[122:123], v[144:145], v[174:175]
	v_pk_fma_f32 v[120:121], v[120:121], v[160:161], v[172:173]
	global_store_dwordx4 v[156:157], v[124:127], off
	global_store_dwordx4 v[156:157], v[120:123], off offset:16
	s_nop 0
	v_or_b32_e32 v146, 16, v134
	v_ashrrev_i32_e32 v147, 31, v146
	v_lshlrev_b64 v[148:149], 11, v[146:147]
	v_lshl_add_u64 v[148:149], s[78:79], 0, v[148:149]
	v_lshl_add_u64 v[148:149], v[148:149], 0, v[138:139]
	s_waitcnt vmcnt(13)
	v_lshlrev_b32_e32 v150, 16, v176
	v_and_b32_e32 v151, 0xffff0000, v176
	v_lshlrev_b32_e32 v120, 16, v177
	v_and_b32_e32 v121, 0xffff0000, v177
	v_lshlrev_b32_e32 v152, 16, v178
	v_and_b32_e32 v153, 0xffff0000, v178
	v_lshlrev_b32_e32 v122, 16, v179
	v_and_b32_e32 v123, 0xffff0000, v179
	s_waitcnt vmcnt(12)
	v_pk_fma_f32 v[114:115], v[114:115], v[120:121], v[182:183]
	v_pk_fma_f32 v[112:113], v[112:113], v[150:151], v[180:181]
	s_waitcnt vmcnt(11)
	v_pk_fma_f32 v[116:117], v[116:117], v[152:153], v[184:185]
	v_pk_fma_f32 v[118:119], v[118:119], v[122:123], v[186:187]
	global_store_dwordx4 v[156:157], v[112:115], off offset:512
	global_store_dwordx4 v[156:157], v[116:119], off offset:528
	s_mov_b64 s[98:99], 0x10000
	v_lshl_add_u64 v[220:221], v[162:163], 0, s[98:99]
	global_load_dwordx4 v[164:167], v[220:221], off offset:256
	s_mov_b64 s[98:99], 0x20000
	v_lshl_add_u64 v[226:227], v[206:207], 0, s[98:99]
	global_load_dwordx4 v[168:171], v[226:227], off offset:512
	global_load_dwordx4 v[172:175], v[226:227], off offset:528
	s_waitcnt vmcnt(15)
	v_lshlrev_b32_e32 v126, 16, v188
	v_lshlrev_b64 v[116:117], 12, v[146:147]
	v_lshl_add_u64 v[116:117], s[10:11], 0, v[116:117]
	v_lshl_add_u64 v[124:125], v[116:117], 0, v[136:137]
	v_and_b32_e32 v127, 0xffff0000, v188
	v_lshlrev_b32_e32 v112, 16, v189
	v_and_b32_e32 v113, 0xffff0000, v189
	v_lshlrev_b32_e32 v142, 16, v190
	v_and_b32_e32 v143, 0xffff0000, v190
	v_lshlrev_b32_e32 v114, 16, v191
	v_and_b32_e32 v115, 0xffff0000, v191
	s_waitcnt vmcnt(14)
	v_pk_fma_f32 v[110:111], v[110:111], v[112:113], v[196:197]
	v_pk_fma_f32 v[108:109], v[108:109], v[126:127], v[194:195]
	s_waitcnt vmcnt(13)
	v_pk_fma_f32 v[106:107], v[106:107], v[114:115], v[204:205]
	v_pk_fma_f32 v[104:105], v[104:105], v[142:143], v[202:203]
	global_store_dwordx4 v[124:125], v[108:111], off
	global_store_dwordx4 v[124:125], v[104:107], off offset:16
	s_mov_b64 s[98:99], 0x18000
	v_lshl_add_u64 v[220:221], v[162:163], 0, s[98:99]
	global_load_dwordx4 v[176:179], v[220:221], off
	s_mov_b64 s[98:99], 0x30000
	v_lshl_add_u64 v[226:227], v[206:207], 0, s[98:99]
	global_load_dwordx4 v[180:183], v[226:227], off
	global_load_dwordx4 v[184:187], v[226:227], off offset:16
	s_nop 0
	v_or_b32_e32 v116, 32, v134
	v_ashrrev_i32_e32 v117, 31, v116
	v_lshlrev_b64 v[118:119], 11, v[116:117]
	v_lshl_add_u64 v[118:119], s[78:79], 0, v[118:119]
	v_lshl_add_u64 v[118:119], v[118:119], 0, v[138:139]
	s_waitcnt vmcnt(17)
;     __device__ __forceinline__ void operator()(const pg8::f32x4 (&acc)[2][2][4][2], const pg8::Unit& u, int wr, int wc, int fr, int fq) const {
;     ...
;         for (int ai = 0; ai < 2; ++ai)
; #pragma unroll
;             for (int m = 0; m < 4; ++m) {
;                 const int row = u.pm * 256 + ai * 128 + wr * 64 + m * 16 + fr;
; #pragma unroll
;                 for (int bj = 0; bj < 2; ++bj) {
;                     const int col = u.pn * 256 + bj * 128 + wc * 32 + 8 * fq;
;                     f(w, row, col, acc[ai][bj][m][0], acc[ai][bj][m][1]);
;                 }
	v_lshlrev_b32_e32 v120, 16, v212
	v_and_b32_e32 v121, 0xffff0000, v212
	v_lshlrev_b32_e32 v104, 16, v213
	v_and_b32_e32 v105, 0xffff0000, v213
	v_lshlrev_b32_e32 v122, 16, v214
	v_and_b32_e32 v123, 0xffff0000, v214
	v_lshlrev_b32_e32 v106, 16, v215
	v_and_b32_e32 v107, 0xffff0000, v215
	s_waitcnt vmcnt(16)
	v_pk_fma_f32 v[98:99], v[98:99], v[104:105], v[218:219]
	v_pk_fma_f32 v[96:97], v[96:97], v[120:121], v[216:217]
	s_waitcnt vmcnt(15)
	v_pk_fma_f32 v[100:101], v[100:101], v[122:123], v[230:231]
	v_pk_fma_f32 v[102:103], v[102:103], v[106:107], v[232:233]
	global_store_dwordx4 v[124:125], v[96:99], off offset:512
	global_store_dwordx4 v[124:125], v[100:103], off offset:528
	s_mov_b64 s[98:99], 0x18000
	v_lshl_add_u64 v[220:221], v[162:163], 0, s[98:99]
	global_load_dwordx4 v[188:191], v[220:221], off offset:256
	s_mov_b64 s[98:99], 0x30000
	v_lshl_add_u64 v[226:227], v[206:207], 0, s[98:99]
	global_load_dwordx4 v[194:197], v[226:227], off offset:512
	global_load_dwordx4 v[202:205], v[226:227], off offset:528
	s_waitcnt vmcnt(19)
	v_lshlrev_b32_e32 v110, 16, v234
	v_lshlrev_b64 v[100:101], 12, v[116:117]
	v_lshl_add_u64 v[100:101], s[10:11], 0, v[100:101]
	v_lshl_add_u64 v[108:109], v[100:101], 0, v[136:137]
	v_and_b32_e32 v111, 0xffff0000, v234
	v_lshlrev_b32_e32 v96, 16, v235
	v_and_b32_e32 v97, 0xffff0000, v235
	v_lshlrev_b32_e32 v112, 16, v236
	v_and_b32_e32 v113, 0xffff0000, v236
	v_lshlrev_b32_e32 v98, 16, v237
	v_and_b32_e32 v99, 0xffff0000, v237
	s_waitcnt vmcnt(18)
	v_pk_fma_f32 v[94:95], v[94:95], v[96:97], v[240:241]
	v_pk_fma_f32 v[92:93], v[92:93], v[110:111], v[238:239]
	s_waitcnt vmcnt(17)
	v_pk_fma_f32 v[90:91], v[90:91], v[98:99], v[244:245]
	v_pk_fma_f32 v[88:89], v[88:89], v[112:113], v[242:243]
	global_store_dwordx4 v[108:109], v[92:95], off
	global_store_dwordx4 v[108:109], v[88:91], off offset:16
	s_mov_b64 s[98:99], 0x40000
	v_lshl_add_u64 v[220:221], v[162:163], 0, s[98:99]
	global_load_dwordx4 v[212:215], v[220:221], off
	s_mov_b64 s[98:99], 0x80000
	v_lshl_add_u64 v[226:227], v[206:207], 0, s[98:99]
	global_load_dwordx4 v[216:219], v[226:227], off
	global_load_dwordx4 v[230:233], v[226:227], off offset:16
	s_nop 0
	v_or_b32_e32 v100, 48, v134
	v_ashrrev_i32_e32 v101, 31, v100
	v_lshlrev_b64 v[102:103], 11, v[100:101]
	v_lshl_add_u64 v[102:103], s[78:79], 0, v[102:103]
	v_lshl_add_u64 v[102:103], v[102:103], 0, v[138:139]
	s_waitcnt vmcnt(17)
	v_lshlrev_b32_e32 v104, 16, v164
	v_and_b32_e32 v105, 0xffff0000, v164
	v_lshlrev_b32_e32 v88, 16, v165
	v_and_b32_e32 v89, 0xffff0000, v165
	v_lshlrev_b32_e32 v106, 16, v166
	v_and_b32_e32 v107, 0xffff0000, v166
	v_lshlrev_b32_e32 v90, 16, v167
	v_and_b32_e32 v91, 0xffff0000, v167
	s_waitcnt vmcnt(16)
	v_pk_fma_f32 v[82:83], v[82:83], v[88:89], v[170:171]
	v_pk_fma_f32 v[80:81], v[80:81], v[104:105], v[168:169]
	s_waitcnt vmcnt(15)
	v_pk_fma_f32 v[84:85], v[84:85], v[106:107], v[172:173]
	v_pk_fma_f32 v[86:87], v[86:87], v[90:91], v[174:175]
	global_store_dwordx4 v[108:109], v[80:83], off offset:512
	global_store_dwordx4 v[108:109], v[84:87], off offset:528
	s_mov_b64 s[98:99], 0x40000
	v_lshl_add_u64 v[220:221], v[162:163], 0, s[98:99]
	global_load_dwordx4 v[234:237], v[220:221], off offset:256
	s_mov_b64 s[98:99], 0x80000
	v_lshl_add_u64 v[226:227], v[206:207], 0, s[98:99]
	global_load_dwordx4 v[238:241], v[226:227], off offset:512
	global_load_dwordx4 v[242:245], v[226:227], off offset:528
	s_waitcnt vmcnt(17)
	v_lshlrev_b32_e32 v94, 16, v176
	v_lshlrev_b64 v[84:85], 12, v[100:101]
	v_lshl_add_u64 v[84:85], s[10:11], 0, v[84:85]
	v_lshl_add_u64 v[92:93], v[84:85], 0, v[136:137]
	v_and_b32_e32 v95, 0xffff0000, v176
	v_lshlrev_b32_e32 v80, 16, v177
	v_and_b32_e32 v81, 0xffff0000, v177
	v_lshlrev_b32_e32 v96, 16, v178
	v_and_b32_e32 v97, 0xffff0000, v178
	v_lshlrev_b32_e32 v82, 16, v179
	v_and_b32_e32 v83, 0xffff0000, v179
	s_waitcnt vmcnt(16)
	v_pk_fma_f32 v[78:79], v[78:79], v[80:81], v[182:183]
	v_pk_fma_f32 v[76:77], v[76:77], v[94:95], v[180:181]
	s_waitcnt vmcnt(15)
	v_pk_fma_f32 v[74:75], v[74:75], v[82:83], v[186:187]
	v_pk_fma_f32 v[72:73], v[72:73], v[96:97], v[184:185]
	global_store_dwordx4 v[92:93], v[76:79], off
	global_store_dwordx4 v[92:93], v[72:75], off offset:16
	s_mov_b64 s[98:99], 0x48000
	v_lshl_add_u64 v[220:221], v[162:163], 0, s[98:99]
	global_load_dwordx4 v[164:167], v[220:221], off
	s_mov_b64 s[98:99], 0x90000
	v_lshl_add_u64 v[226:227], v[206:207], 0, s[98:99]
	global_load_dwordx4 v[168:171], v[226:227], off
	global_load_dwordx4 v[172:175], v[226:227], off offset:16
	s_nop 0
	v_add_u32_e32 v84, 0x80, v134
	v_ashrrev_i32_e32 v85, 31, v84
	v_lshlrev_b64 v[86:87], 11, v[84:85]
	v_lshl_add_u64 v[86:87], s[78:79], 0, v[86:87]
	v_lshl_add_u64 v[86:87], v[86:87], 0, v[138:139]
	s_waitcnt vmcnt(17)
	v_lshlrev_b32_e32 v88, 16, v188
	v_and_b32_e32 v89, 0xffff0000, v188
	v_lshlrev_b32_e32 v72, 16, v189
	v_and_b32_e32 v73, 0xffff0000, v189
	v_lshlrev_b32_e32 v90, 16, v190
	v_and_b32_e32 v91, 0xffff0000, v190
	v_lshlrev_b32_e32 v74, 16, v191
	v_and_b32_e32 v75, 0xffff0000, v191
	s_waitcnt vmcnt(16)
	v_pk_fma_f32 v[62:63], v[62:63], v[72:73], v[196:197]
	v_pk_fma_f32 v[60:61], v[60:61], v[88:89], v[194:195]
	s_waitcnt vmcnt(15)
	v_pk_fma_f32 v[64:65], v[64:65], v[90:91], v[202:203]
	v_pk_fma_f32 v[66:67], v[66:67], v[74:75], v[204:205]
	global_store_dwordx4 v[92:93], v[60:63], off offset:512
	global_store_dwordx4 v[92:93], v[64:67], off offset:528
	s_mov_b64 s[98:99], 0x48000
	v_lshl_add_u64 v[220:221], v[162:163], 0, s[98:99]
	global_load_dwordx4 v[176:179], v[220:221], off offset:256
	s_mov_b64 s[98:99], 0x90000
	v_lshl_add_u64 v[226:227], v[206:207], 0, s[98:99]
	global_load_dwordx4 v[180:183], v[226:227], off offset:512
	global_load_dwordx4 v[184:187], v[226:227], off offset:528
	s_waitcnt vmcnt(17)
;     __device__ __forceinline__ void operator()(const pg8::f32x4 (&acc)[2][2][4][2], const pg8::Unit& u, int wr, int wc, int fr, int fq) const {
;     ...
;         for (int ai = 0; ai < 2; ++ai)
; #pragma unroll
;             for (int m = 0; m < 4; ++m) {
;                 const int row = u.pm * 256 + ai * 128 + wr * 64 + m * 16 + fr;
; #pragma unroll
;                 for (int bj = 0; bj < 2; ++bj) {
;                     const int col = u.pn * 256 + bj * 128 + wc * 32 + 8 * fq;
;                     f(w, row, col, acc[ai][bj][m][0], acc[ai][bj][m][1]);
;                 }
	v_lshlrev_b32_e32 v78, 16, v212
	v_lshlrev_b64 v[64:65], 12, v[84:85]
	v_lshl_add_u64 v[64:65], s[10:11], 0, v[64:65]
	v_lshl_add_u64 v[76:77], v[64:65], 0, v[136:137]
	v_and_b32_e32 v79, 0xffff0000, v212
	v_lshlrev_b32_e32 v60, 16, v213
	v_and_b32_e32 v61, 0xffff0000, v213
	v_lshlrev_b32_e32 v80, 16, v214
	v_and_b32_e32 v81, 0xffff0000, v214
	v_lshlrev_b32_e32 v82, 16, v215
	v_and_b32_e32 v83, 0xffff0000, v215
	s_waitcnt vmcnt(16)
	v_pk_fma_f32 v[62:63], v[70:71], v[60:61], v[218:219]
	v_pk_fma_f32 v[60:61], v[68:69], v[78:79], v[216:217]
	s_waitcnt vmcnt(15)
	v_pk_fma_f32 v[58:59], v[58:59], v[82:83], v[232:233]
	v_pk_fma_f32 v[56:57], v[56:57], v[80:81], v[230:231]
	global_store_dwordx4 v[76:77], v[60:63], off
	global_store_dwordx4 v[76:77], v[56:59], off offset:16
	s_mov_b64 s[98:99], 0x50000
	v_lshl_add_u64 v[220:221], v[162:163], 0, s[98:99]
	global_load_dwordx4 v[188:191], v[220:221], off
	s_mov_b64 s[98:99], 0xa0000
	v_lshl_add_u64 v[226:227], v[206:207], 0, s[98:99]
	global_load_dwordx4 v[194:197], v[226:227], off
	global_load_dwordx4 v[202:205], v[226:227], off offset:16
	s_nop 0
	v_add_u32_e32 v68, 0x90, v134
	v_ashrrev_i32_e32 v69, 31, v68
	v_lshlrev_b64 v[70:71], 11, v[68:69]
	v_lshl_add_u64 v[70:71], s[78:79], 0, v[70:71]
	v_lshl_add_u64 v[70:71], v[70:71], 0, v[138:139]
	s_waitcnt vmcnt(17)
	v_lshlrev_b32_e32 v72, 16, v234
	v_and_b32_e32 v73, 0xffff0000, v234
	v_lshlrev_b32_e32 v56, 16, v235
	v_and_b32_e32 v57, 0xffff0000, v235
	v_lshlrev_b32_e32 v74, 16, v236
	v_and_b32_e32 v75, 0xffff0000, v236
	v_lshlrev_b32_e32 v58, 16, v237
	v_and_b32_e32 v59, 0xffff0000, v237
	s_waitcnt vmcnt(16)
	v_pk_fma_f32 v[50:51], v[50:51], v[56:57], v[240:241]
	v_pk_fma_f32 v[48:49], v[48:49], v[72:73], v[238:239]
	s_waitcnt vmcnt(15)
	v_pk_fma_f32 v[52:53], v[52:53], v[74:75], v[242:243]
	v_pk_fma_f32 v[54:55], v[54:55], v[58:59], v[244:245]
	global_store_dwordx4 v[76:77], v[48:51], off offset:512
	global_store_dwordx4 v[76:77], v[52:55], off offset:528
	s_mov_b64 s[98:99], 0x50000
	v_lshl_add_u64 v[220:221], v[162:163], 0, s[98:99]
	global_load_dwordx4 v[212:215], v[220:221], off offset:256
	s_mov_b64 s[98:99], 0xa0000
	v_lshl_add_u64 v[226:227], v[206:207], 0, s[98:99]
	global_load_dwordx4 v[216:219], v[226:227], off offset:512
	global_load_dwordx4 v[230:233], v[226:227], off offset:528
	s_waitcnt vmcnt(17)
	v_lshlrev_b32_e32 v62, 16, v164
	v_lshlrev_b64 v[52:53], 12, v[68:69]
	v_lshl_add_u64 v[52:53], s[10:11], 0, v[52:53]
	v_lshl_add_u64 v[60:61], v[52:53], 0, v[136:137]
	v_and_b32_e32 v63, 0xffff0000, v164
	v_lshlrev_b32_e32 v48, 16, v165
	v_and_b32_e32 v49, 0xffff0000, v165
	v_lshlrev_b32_e32 v64, 16, v166
	v_and_b32_e32 v65, 0xffff0000, v166
	v_lshlrev_b32_e32 v50, 16, v167
	v_and_b32_e32 v51, 0xffff0000, v167
	s_waitcnt vmcnt(16)
	v_pk_fma_f32 v[46:47], v[46:47], v[48:49], v[170:171]
	v_pk_fma_f32 v[44:45], v[44:45], v[62:63], v[168:169]
	s_waitcnt vmcnt(15)
	v_pk_fma_f32 v[42:43], v[42:43], v[50:51], v[174:175]
	v_pk_fma_f32 v[40:41], v[40:41], v[64:65], v[172:173]
	global_store_dwordx4 v[60:61], v[44:47], off
	global_store_dwordx4 v[60:61], v[40:43], off offset:16
	s_mov_b64 s[98:99], 0x58000
	v_lshl_add_u64 v[220:221], v[162:163], 0, s[98:99]
	global_load_dwordx4 v[234:237], v[220:221], off
	s_mov_b64 s[98:99], 0xb0000
	v_lshl_add_u64 v[226:227], v[206:207], 0, s[98:99]
	global_load_dwordx4 v[238:241], v[226:227], off
	global_load_dwordx4 v[242:245], v[226:227], off offset:16
	s_nop 0
	v_add_u32_e32 v52, 0xa0, v134
	v_ashrrev_i32_e32 v53, 31, v52
	v_lshlrev_b64 v[54:55], 11, v[52:53]
	v_lshl_add_u64 v[54:55], s[78:79], 0, v[54:55]
	v_lshl_add_u64 v[54:55], v[54:55], 0, v[138:139]
	s_waitcnt vmcnt(17)
	v_lshlrev_b32_e32 v56, 16, v176
	v_and_b32_e32 v57, 0xffff0000, v176
	v_lshlrev_b32_e32 v40, 16, v177
	v_and_b32_e32 v41, 0xffff0000, v177
	v_lshlrev_b32_e32 v58, 16, v178
	v_and_b32_e32 v59, 0xffff0000, v178
	v_lshlrev_b32_e32 v42, 16, v179
	v_and_b32_e32 v43, 0xffff0000, v179
	s_waitcnt vmcnt(16)
;     __device__ __forceinline__ void operator()(const pg8::f32x4 (&acc)[2][2][4][2], const pg8::Unit& u, int wr, int wc, int fr, int fq) const {
;     ...
;         for (int ai = 0; ai < 2; ++ai)
; #pragma unroll
;             for (int m = 0; m < 4; ++m) {
;                 const int row = u.pm * 256 + ai * 128 + wr * 64 + m * 16 + fr;
; #pragma unroll
;                 for (int bj = 0; bj < 2; ++bj) {
;                     const int col = u.pn * 256 + bj * 128 + wc * 32 + 8 * fq;
;                     f(w, row, col, acc[ai][bj][m][0], acc[ai][bj][m][1]);
;                 }
	v_pk_fma_f32 v[34:35], v[34:35], v[40:41], v[182:183]
	v_pk_fma_f32 v[32:33], v[32:33], v[56:57], v[180:181]
	s_waitcnt vmcnt(15)
	v_pk_fma_f32 v[36:37], v[36:37], v[58:59], v[184:185]
	v_pk_fma_f32 v[38:39], v[38:39], v[42:43], v[186:187]
	global_store_dwordx4 v[60:61], v[32:35], off offset:512
	global_store_dwordx4 v[60:61], v[36:39], off offset:528
	s_mov_b64 s[98:99], 0x58000
	v_lshl_add_u64 v[220:221], v[162:163], 0, s[98:99]
	global_load_dwordx4 v[164:167], v[220:221], off offset:256
	s_mov_b64 s[98:99], 0xb0000
	v_lshl_add_u64 v[226:227], v[206:207], 0, s[98:99]
	global_load_dwordx4 v[168:171], v[226:227], off offset:512
	global_load_dwordx4 v[172:175], v[226:227], off offset:528
	s_waitcnt vmcnt(17)
	v_lshlrev_b32_e32 v46, 16, v188
	v_lshlrev_b64 v[36:37], 12, v[52:53]
	v_lshl_add_u64 v[36:37], s[10:11], 0, v[36:37]
	v_lshl_add_u64 v[44:45], v[36:37], 0, v[136:137]
	v_and_b32_e32 v47, 0xffff0000, v188
	v_lshlrev_b32_e32 v32, 16, v189
	v_and_b32_e32 v33, 0xffff0000, v189
	v_lshlrev_b32_e32 v48, 16, v190
	v_and_b32_e32 v49, 0xffff0000, v190
	v_lshlrev_b32_e32 v34, 16, v191
	v_and_b32_e32 v35, 0xffff0000, v191
	s_waitcnt vmcnt(16)
	v_pk_fma_f32 v[30:31], v[30:31], v[32:33], v[196:197]
	v_pk_fma_f32 v[28:29], v[28:29], v[46:47], v[194:195]
	s_waitcnt vmcnt(15)
	v_pk_fma_f32 v[26:27], v[26:27], v[34:35], v[204:205]
	v_pk_fma_f32 v[24:25], v[24:25], v[48:49], v[202:203]
	global_store_dwordx4 v[44:45], v[28:31], off
	global_store_dwordx4 v[44:45], v[24:27], off offset:16
	s_nop 0
	v_add_u32_e32 v36, 0xb0, v134
	v_ashrrev_i32_e32 v37, 31, v36
	v_lshlrev_b64 v[38:39], 11, v[36:37]
	v_lshl_add_u64 v[38:39], s[78:79], 0, v[38:39]
	v_lshl_add_u64 v[38:39], v[38:39], 0, v[138:139]
	s_waitcnt vmcnt(14)
	v_lshlrev_b32_e32 v40, 16, v212
	v_and_b32_e32 v41, 0xffff0000, v212
	v_lshlrev_b32_e32 v24, 16, v213
	v_and_b32_e32 v25, 0xffff0000, v213
	v_lshlrev_b32_e32 v42, 16, v214
	v_and_b32_e32 v43, 0xffff0000, v214
	v_lshlrev_b32_e32 v26, 16, v215
	v_and_b32_e32 v27, 0xffff0000, v215
	s_waitcnt vmcnt(13)
	v_pk_fma_f32 v[18:19], v[18:19], v[24:25], v[218:219]
	v_pk_fma_f32 v[16:17], v[16:17], v[40:41], v[216:217]
	s_waitcnt vmcnt(12)
	v_pk_fma_f32 v[20:21], v[20:21], v[42:43], v[230:231]
	v_pk_fma_f32 v[22:23], v[22:23], v[26:27], v[232:233]
	global_store_dwordx4 v[44:45], v[16:19], off offset:512
	global_store_dwordx4 v[44:45], v[20:23], off offset:528
	s_waitcnt vmcnt(11)
	v_lshlrev_b32_e32 v30, 16, v234
	s_nop 1
	v_lshlrev_b64 v[20:21], 12, v[36:37]
	v_lshl_add_u64 v[20:21], s[10:11], 0, v[20:21]
	v_lshl_add_u64 v[28:29], v[20:21], 0, v[136:137]
	v_and_b32_e32 v31, 0xffff0000, v234
	v_lshlrev_b32_e32 v16, 16, v235
	v_and_b32_e32 v17, 0xffff0000, v235
	v_lshlrev_b32_e32 v32, 16, v236
	v_and_b32_e32 v33, 0xffff0000, v236
	v_lshlrev_b32_e32 v18, 16, v237
	v_and_b32_e32 v19, 0xffff0000, v237
	s_waitcnt vmcnt(10)
	v_pk_fma_f32 v[14:15], v[14:15], v[16:17], v[240:241]
	v_pk_fma_f32 v[12:13], v[12:13], v[30:31], v[238:239]
	s_waitcnt vmcnt(9)
	v_pk_fma_f32 v[10:11], v[10:11], v[18:19], v[244:245]
	v_pk_fma_f32 v[8:9], v[8:9], v[32:33], v[242:243]
	global_store_dwordx4 v[28:29], v[12:15], off
	global_store_dwordx4 v[28:29], v[8:11], off offset:16
	s_nop 0
	s_waitcnt vmcnt(8)
	v_lshlrev_b32_e32 v20, 16, v164
	v_and_b32_e32 v21, 0xffff0000, v164
	v_lshlrev_b32_e32 v8, 16, v165
	v_and_b32_e32 v9, 0xffff0000, v165
	v_lshlrev_b32_e32 v22, 16, v166
	v_and_b32_e32 v23, 0xffff0000, v166
	v_lshlrev_b32_e32 v10, 16, v167
	v_and_b32_e32 v11, 0xffff0000, v167
	s_waitcnt vmcnt(7)
	v_pk_fma_f32 v[2:3], v[2:3], v[8:9], v[170:171]
	v_pk_fma_f32 v[0:1], v[0:1], v[20:21], v[168:169]
	s_waitcnt vmcnt(6)
	v_pk_fma_f32 v[6:7], v[6:7], v[10:11], v[174:175]
	v_pk_fma_f32 v[4:5], v[4:5], v[22:23], v[172:173]
	global_store_dwordx4 v[28:29], v[0:3], off offset:512
	global_store_dwordx4 v[28:29], v[4:7], off offset:528
	s_load_dword s75, s[96:97], 0x0
	s_cbranch_vccnz .LBB0_54
	s_andn2_b64 vcc, exec, s[14:15]
	s_cbranch_vccnz .LBB0_53
	s_barrier
	s_branch .LBB0_53
